# grid barrier: L1 invalidate only in front of phases 5, 7, 8, 10 (the only phases that re-read a buffer this launch read earlier and another CU rewrote since)
# speedup vs baseline: 1.0123x; 1.0123x over previous
.LBB0_916:
	s_mov_b32 s101, 0
	s_cmp_eq_u32 s76, 5
	s_cbranch_scc1 .Lxb_inv
	s_cmp_eq_u32 s76, 7
	s_cbranch_scc1 .Lxb_inv
	s_cmp_eq_u32 s76, 8
	s_cbranch_scc1 .Lxb_inv
	s_cmp_lg_u32 s76, 10
	s_cbranch_scc1 .Lxb_noinv
